# final norm: second-row slab fold batched too (code after it kept at its previous alignment)
# baseline (speedup 1.0000x reference)
; __device__ __forceinline__ void phase_norm(PP P, int l, int which, int nsl, const float* fgate, float fscale, const Ids I) {
;     ...
;         const int rows[2] = {row0, (row0 + nw < MT) ? row0 + nw : row0};
;         f32x4 v[2][4]; float ss[2];
; #pragma unroll
;         for (int j = 0; j < 2; ++j) { const int row = rows[j];
;             const float* xr = from_in ? (row < MTP ? P->in[I_XP] + (size_t)row * D : P->in[I_XS] + (size_t)(row - MTP) * D) : xb + (size_t)row * D;
; #pragma unroll
;             for (int i = 0; i < 4; ++i) v[j][i] = *(const f32x4*)(xr + lane * 4 + 256 * i);
;             if (nsl > 0 && row >= MTP && !(j == 1 && row == row0)) {
;                 const float* pp = (const float*)(P->ws + WS_R2) + (size_t)(row - MTP) * D + lane * 4; const float* gp = fgate + (size_t)mod_row(row) * 9216 + lane * 4;
; #pragma unroll
;                 for (int i = 0; i < 4; ++i) { f32x4 a = (f32x4){0.f, 0.f, 0.f, 0.f};
;                     for (int sl = 0; sl < nsl; ++sl) a += *(const f32x4*)(pp + (size_t)sl * MTS * D + 256 * i);
;                     v[j][i] += (*(const f32x4*)(gp + 256 * i) * fscale) * a;
.LBB0_23:
	s_add_i32 s6, s44, s54
	s_addk_i32 s6, 0x4000
	s_cmpk_lt_i32 s6, 0x4200
	s_cselect_b32 s8, s6, s3
	s_ashr_i32 s9, s8, 31
	s_lshl_b64 s[6:7], s[8:9], 12
	v_lshl_add_u64 v[46:47], v[42:43], 0, s[6:7]
	global_load_dwordx4 v[28:31], v[46:47], off
	global_load_dwordx4 v[24:27], v[46:47], off offset:1024
	global_load_dwordx4 v[20:23], v[46:47], off offset:2048
	global_load_dwordx4 v[16:19], v[46:47], off offset:3072
	s_cmpk_lt_i32 s8, 0x4000
	s_cselect_b64 s[12:13], -1, 0
	s_cmp_lg_u32 s3, s8
	s_cselect_b64 s[6:7], -1, 0
	s_cmp_eq_u32 s3, s8
	s_cselect_b64 s[14:15], -1, 0
	s_or_b64 s[12:13], s[12:13], s[14:15]
	s_and_b64 vcc, exec, s[12:13]
	s_cbranch_vccnz .LBB0_25
	s_addk_i32 s8, 0xc000
	s_mov_b32 s9, s55
	s_lshl_b64 s[12:13], s[8:9], 12
	v_lshl_add_u64 v[48:49], v[36:37], 0, s[12:13]
	s_lshr_b32 s3, s8, 2
	s_add_i32 s3, s3, 8
	v_mad_u64_u32 v[32:33], s[8:9], s3, v184, v[38:39]
	global_load_dwordx4 v[152:155], v[32:33], off
	global_load_dwordx4 v[156:159], v[32:33], off offset:1024
	global_load_dwordx4 v[160:163], v[32:33], off offset:2048
	global_load_dwordx4 v[164:167], v[32:33], off offset:3072
	v_mov_b32_e32 v34, v48
	v_mov_b32_e32 v35, v49
	global_load_dwordx4 v[92:95], v[34:35], off
	global_load_dwordx4 v[188:191], v[34:35], off offset:1024
	v_lshl_add_u64 v[34:35], v[34:35], 0, s[82:83]
	global_load_dwordx4 v[96:99], v[34:35], off
	global_load_dwordx4 v[192:195], v[34:35], off offset:1024
	v_lshl_add_u64 v[34:35], v[34:35], 0, s[82:83]
	global_load_dwordx4 v[100:103], v[34:35], off
	global_load_dwordx4 v[196:199], v[34:35], off offset:1024
	v_lshl_add_u64 v[34:35], v[34:35], 0, s[82:83]
	global_load_dwordx4 v[104:107], v[34:35], off
	global_load_dwordx4 v[200:203], v[34:35], off offset:1024
	v_lshl_add_u64 v[34:35], v[34:35], 0, s[82:83]
	global_load_dwordx4 v[108:111], v[34:35], off
	global_load_dwordx4 v[204:207], v[34:35], off offset:1024
	v_lshl_add_u64 v[34:35], v[34:35], 0, s[82:83]
	global_load_dwordx4 v[112:115], v[34:35], off
	global_load_dwordx4 v[208:211], v[34:35], off offset:1024
	v_lshl_add_u64 v[34:35], v[34:35], 0, s[82:83]
	global_load_dwordx4 v[116:119], v[34:35], off
	global_load_dwordx4 v[212:215], v[34:35], off offset:1024
	v_lshl_add_u64 v[34:35], v[34:35], 0, s[82:83]
	global_load_dwordx4 v[120:123], v[34:35], off
	global_load_dwordx4 v[216:219], v[34:35], off offset:1024
	v_lshl_add_u64 v[34:35], v[34:35], 0, s[82:83]
	global_load_dwordx4 v[124:127], v[34:35], off
	global_load_dwordx4 v[220:223], v[34:35], off offset:1024
	v_lshl_add_u64 v[34:35], v[34:35], 0, s[82:83]
	global_load_dwordx4 v[128:131], v[34:35], off
	global_load_dwordx4 v[224:227], v[34:35], off offset:1024
	v_lshl_add_u64 v[34:35], v[34:35], 0, s[82:83]
	global_load_dwordx4 v[132:135], v[34:35], off
	global_load_dwordx4 v[228:231], v[34:35], off offset:1024
	v_mov_b32_e32 v136, 0
	v_mov_b32_e32 v137, 0
	v_mov_b32_e32 v138, 0
	v_mov_b32_e32 v139, 0
	v_mov_b32_e32 v140, 0
	v_mov_b32_e32 v141, 0
	v_mov_b32_e32 v142, 0
	v_mov_b32_e32 v143, 0
	s_waitcnt vmcnt(0)
	v_pk_add_f32 v[138:139], v[138:139], v[94:95]
	v_pk_add_f32 v[136:137], v[136:137], v[92:93]
	v_pk_add_f32 v[142:143], v[142:143], v[190:191]
	v_pk_add_f32 v[140:141], v[140:141], v[188:189]
	v_pk_add_f32 v[138:139], v[138:139], v[98:99]
	v_pk_add_f32 v[136:137], v[136:137], v[96:97]
	v_pk_add_f32 v[142:143], v[142:143], v[194:195]
	v_pk_add_f32 v[140:141], v[140:141], v[192:193]
	v_pk_add_f32 v[138:139], v[138:139], v[102:103]
	v_pk_add_f32 v[136:137], v[136:137], v[100:101]
	v_pk_add_f32 v[142:143], v[142:143], v[198:199]
	v_pk_add_f32 v[140:141], v[140:141], v[196:197]
	v_pk_add_f32 v[138:139], v[138:139], v[106:107]
	v_pk_add_f32 v[136:137], v[136:137], v[104:105]
	v_pk_add_f32 v[142:143], v[142:143], v[202:203]
	v_pk_add_f32 v[140:141], v[140:141], v[200:201]
	v_pk_add_f32 v[138:139], v[138:139], v[110:111]
	v_pk_add_f32 v[136:137], v[136:137], v[108:109]
	v_pk_add_f32 v[142:143], v[142:143], v[206:207]
	v_pk_add_f32 v[140:141], v[140:141], v[204:205]
	v_pk_add_f32 v[138:139], v[138:139], v[114:115]
	v_pk_add_f32 v[136:137], v[136:137], v[112:113]
	v_pk_add_f32 v[142:143], v[142:143], v[210:211]
	v_pk_add_f32 v[140:141], v[140:141], v[208:209]
	v_pk_add_f32 v[138:139], v[138:139], v[118:119]
	v_pk_add_f32 v[136:137], v[136:137], v[116:117]
	v_pk_add_f32 v[142:143], v[142:143], v[214:215]
	v_pk_add_f32 v[140:141], v[140:141], v[212:213]
	v_pk_add_f32 v[138:139], v[138:139], v[122:123]
	v_pk_add_f32 v[136:137], v[136:137], v[120:121]
	v_pk_add_f32 v[142:143], v[142:143], v[218:219]
	v_pk_add_f32 v[140:141], v[140:141], v[216:217]
	v_pk_add_f32 v[138:139], v[138:139], v[126:127]
	v_pk_add_f32 v[136:137], v[136:137], v[124:125]
	v_pk_add_f32 v[142:143], v[142:143], v[222:223]
	v_pk_add_f32 v[140:141], v[140:141], v[220:221]
	v_pk_add_f32 v[138:139], v[138:139], v[130:131]
	v_pk_add_f32 v[136:137], v[136:137], v[128:129]
	v_pk_add_f32 v[142:143], v[142:143], v[226:227]
	v_pk_add_f32 v[140:141], v[140:141], v[224:225]
	v_pk_add_f32 v[138:139], v[138:139], v[134:135]
	v_pk_add_f32 v[136:137], v[136:137], v[132:133]
	v_pk_add_f32 v[142:143], v[142:143], v[230:231]
	v_pk_add_f32 v[140:141], v[140:141], v[228:229]
	v_pk_mul_f32 v[154:155], v[154:155], 0.5 op_sel_hi:[1,0]
; __device__ __forceinline__ void phase_norm(PP P, int l, int which, int nsl, const float* fgate, float fscale, const Ids I) {
;     ...
;                 for (int i = 0; i < 4; ++i) { f32x4 a = (f32x4){0.f, 0.f, 0.f, 0.f};
;                     for (int sl = 0; sl < nsl; ++sl) a += *(const f32x4*)(pp + (size_t)sl * MTS * D + 256 * i);
;                     v[j][i] += (*(const f32x4*)(gp + 256 * i) * fscale) * a;
	v_pk_mul_f32 v[152:153], v[152:153], 0.5 op_sel_hi:[1,0]
	v_pk_fma_f32 v[30:31], v[138:139], v[154:155], v[30:31]
	v_pk_fma_f32 v[28:29], v[136:137], v[152:153], v[28:29]
	v_pk_mul_f32 v[158:159], v[158:159], 0.5 op_sel_hi:[1,0]
	v_pk_mul_f32 v[156:157], v[156:157], 0.5 op_sel_hi:[1,0]
	v_pk_fma_f32 v[26:27], v[142:143], v[158:159], v[26:27]
	v_pk_fma_f32 v[24:25], v[140:141], v[156:157], v[24:25]
	v_mov_b32_e32 v34, v48
	v_mov_b32_e32 v35, v49
	global_load_dwordx4 v[92:95], v[34:35], off offset:2048
	global_load_dwordx4 v[188:191], v[34:35], off offset:3072
	v_lshl_add_u64 v[34:35], v[34:35], 0, s[82:83]
	global_load_dwordx4 v[96:99], v[34:35], off offset:2048
	global_load_dwordx4 v[192:195], v[34:35], off offset:3072
	v_lshl_add_u64 v[34:35], v[34:35], 0, s[82:83]
	global_load_dwordx4 v[100:103], v[34:35], off offset:2048
	global_load_dwordx4 v[196:199], v[34:35], off offset:3072
	v_lshl_add_u64 v[34:35], v[34:35], 0, s[82:83]
	global_load_dwordx4 v[104:107], v[34:35], off offset:2048
	global_load_dwordx4 v[200:203], v[34:35], off offset:3072
	v_lshl_add_u64 v[34:35], v[34:35], 0, s[82:83]
	global_load_dwordx4 v[108:111], v[34:35], off offset:2048
	global_load_dwordx4 v[204:207], v[34:35], off offset:3072
	v_lshl_add_u64 v[34:35], v[34:35], 0, s[82:83]
	global_load_dwordx4 v[112:115], v[34:35], off offset:2048
	global_load_dwordx4 v[208:211], v[34:35], off offset:3072
	v_lshl_add_u64 v[34:35], v[34:35], 0, s[82:83]
	global_load_dwordx4 v[116:119], v[34:35], off offset:2048
	global_load_dwordx4 v[212:215], v[34:35], off offset:3072
	v_lshl_add_u64 v[34:35], v[34:35], 0, s[82:83]
	global_load_dwordx4 v[120:123], v[34:35], off offset:2048
	global_load_dwordx4 v[216:219], v[34:35], off offset:3072
	v_lshl_add_u64 v[34:35], v[34:35], 0, s[82:83]
	global_load_dwordx4 v[124:127], v[34:35], off offset:2048
	global_load_dwordx4 v[220:223], v[34:35], off offset:3072
	v_lshl_add_u64 v[34:35], v[34:35], 0, s[82:83]
	global_load_dwordx4 v[128:131], v[34:35], off offset:2048
	global_load_dwordx4 v[224:227], v[34:35], off offset:3072
	v_lshl_add_u64 v[34:35], v[34:35], 0, s[82:83]
	global_load_dwordx4 v[132:135], v[34:35], off offset:2048
	global_load_dwordx4 v[228:231], v[34:35], off offset:3072
	v_mov_b32_e32 v136, 0
	v_mov_b32_e32 v137, 0
	v_mov_b32_e32 v138, 0
	v_mov_b32_e32 v139, 0
	v_mov_b32_e32 v140, 0
	v_mov_b32_e32 v141, 0
	v_mov_b32_e32 v142, 0
	v_mov_b32_e32 v143, 0
	s_waitcnt vmcnt(0)
	v_pk_add_f32 v[138:139], v[138:139], v[94:95]
	v_pk_add_f32 v[136:137], v[136:137], v[92:93]
	v_pk_add_f32 v[142:143], v[142:143], v[190:191]
	v_pk_add_f32 v[140:141], v[140:141], v[188:189]
	v_pk_add_f32 v[138:139], v[138:139], v[98:99]
	v_pk_add_f32 v[136:137], v[136:137], v[96:97]
	v_pk_add_f32 v[142:143], v[142:143], v[194:195]
	v_pk_add_f32 v[140:141], v[140:141], v[192:193]
	v_pk_add_f32 v[138:139], v[138:139], v[102:103]
	v_pk_add_f32 v[136:137], v[136:137], v[100:101]
	v_pk_add_f32 v[142:143], v[142:143], v[198:199]
	v_pk_add_f32 v[140:141], v[140:141], v[196:197]
	v_pk_add_f32 v[138:139], v[138:139], v[106:107]
	v_pk_add_f32 v[136:137], v[136:137], v[104:105]
	v_pk_add_f32 v[142:143], v[142:143], v[202:203]
	v_pk_add_f32 v[140:141], v[140:141], v[200:201]
	v_pk_add_f32 v[138:139], v[138:139], v[110:111]
	v_pk_add_f32 v[136:137], v[136:137], v[108:109]
	v_pk_add_f32 v[142:143], v[142:143], v[206:207]
	v_pk_add_f32 v[140:141], v[140:141], v[204:205]
	v_pk_add_f32 v[138:139], v[138:139], v[114:115]
	v_pk_add_f32 v[136:137], v[136:137], v[112:113]
	v_pk_add_f32 v[142:143], v[142:143], v[210:211]
	v_pk_add_f32 v[140:141], v[140:141], v[208:209]
	v_pk_add_f32 v[138:139], v[138:139], v[118:119]
	v_pk_add_f32 v[136:137], v[136:137], v[116:117]
	v_pk_add_f32 v[142:143], v[142:143], v[214:215]
	v_pk_add_f32 v[140:141], v[140:141], v[212:213]
	v_pk_add_f32 v[138:139], v[138:139], v[122:123]
	v_pk_add_f32 v[136:137], v[136:137], v[120:121]
	v_pk_add_f32 v[142:143], v[142:143], v[218:219]
	v_pk_add_f32 v[140:141], v[140:141], v[216:217]
	v_pk_add_f32 v[138:139], v[138:139], v[126:127]
	v_pk_add_f32 v[136:137], v[136:137], v[124:125]
	v_pk_add_f32 v[142:143], v[142:143], v[222:223]
	v_pk_add_f32 v[140:141], v[140:141], v[220:221]
	v_pk_add_f32 v[138:139], v[138:139], v[130:131]
	v_pk_add_f32 v[136:137], v[136:137], v[128:129]
	v_pk_add_f32 v[142:143], v[142:143], v[226:227]
	v_pk_add_f32 v[140:141], v[140:141], v[224:225]
	v_pk_add_f32 v[138:139], v[138:139], v[134:135]
	v_pk_add_f32 v[136:137], v[136:137], v[132:133]
	v_pk_add_f32 v[142:143], v[142:143], v[230:231]
	v_pk_add_f32 v[140:141], v[140:141], v[228:229]
	v_pk_mul_f32 v[162:163], v[162:163], 0.5 op_sel_hi:[1,0]
	v_pk_mul_f32 v[160:161], v[160:161], 0.5 op_sel_hi:[1,0]
	v_pk_fma_f32 v[22:23], v[138:139], v[162:163], v[22:23]
	v_pk_fma_f32 v[20:21], v[136:137], v[160:161], v[20:21]
	v_pk_mul_f32 v[166:167], v[166:167], 0.5 op_sel_hi:[1,0]
	v_pk_mul_f32 v[164:165], v[164:165], 0.5 op_sel_hi:[1,0]
	v_pk_fma_f32 v[18:19], v[142:143], v[166:167], v[18:19]
	v_pk_fma_f32 v[16:17], v[140:141], v[164:165], v[16:17]
	s_nop 0
	s_nop 0
	s_nop 0
	s_nop 0
	s_nop 0
	s_nop 0
	s_nop 0
	s_nop 0
	s_nop 0
	s_nop 0
	s_nop 0
	s_nop 0
	s_nop 0
	s_nop 0
	s_nop 0
	s_nop 0
	s_nop 0
	s_nop 0
	s_nop 0
	s_nop 0
	s_nop 0
	s_nop 0
	s_nop 0
	s_nop 0
	s_nop 0
